# phase 6: sample-row final RMSNorm spread over 128 workgroups (wave 0, 4 rows each) instead of 16 workgroups x 8 waves
# speedup vs baseline: 1.0093x; 1.0093x over previous
.LBB0_1183:
	s_cmp_gt_i32 s84, 6
	s_cselect_b64 s[4:5], -1, 0
	s_cmp_lt_i32 s85, 7
	s_cselect_b64 s[6:7], -1, 0
	s_or_b64 s[4:5], s[4:5], s[6:7]
	s_and_b64 vcc, exec, s[4:5]
	s_cbranch_vccnz .LBB0_1187
	s_cmpk_eq_i32 s30, 0x100
	s_cselect_b32 s3, 0x4000, 0
	s_lshl_b32 s2, s2, 2
	v_lshrrev_b32_e32 v0, 6, v170
	v_lshlrev_b32_e32 v0, 10, v0
	s_add_i32 s3, s3, s2
	v_add_u32_e32 v80, s3, v0
	s_movk_i32 s2, 0x4200
	v_cmp_gt_i32_e32 vcc, s2, v80
	s_and_saveexec_b64 s[2:3], vcc
	s_cbranch_execz .LBB0_1187
	s_load_dwordx4 s[4:7], s[0:1], 0x78
	v_lshlrev_b32_e32 v0, 4, v170
	v_and_b32_e32 v16, 0x3f0, v0
	v_ashrrev_i32_e32 v81, 31, v80
	s_lshl_b32 s0, s30, 5
	s_waitcnt lgkmcnt(0)
	global_load_dwordx4 v[0:3], v16, s[4:5]
	global_load_dwordx4 v[4:7], v16, s[4:5] offset:1024
	global_load_dwordx4 v[8:11], v16, s[4:5] offset:2048
	global_load_dwordx4 v[12:15], v16, s[4:5] offset:3072
	v_mbcnt_lo_u32_b32 v16, -1, 0
	v_mbcnt_hi_u32_b32 v16, -1, v16
	v_and_b32_e32 v17, 64, v16
	v_add_u32_e32 v17, 64, v17
	v_xor_b32_e32 v18, 1, v16
	v_cmp_lt_i32_e32 vcc, v18, v17
	s_mov_b64 s[2:3], 0x3c00
	s_ashr_i32 s1, s0, 31
	v_cndmask_b32_e32 v18, v16, v18, vcc
	v_lshlrev_b32_e32 v92, 2, v18
	v_xor_b32_e32 v18, 2, v16
	v_cmp_lt_i32_e32 vcc, v18, v17
	s_mov_b32 s8, 0x358637bd
	s_mov_b64 s[4:5], 0
	v_cndmask_b32_e32 v18, v16, v18, vcc
	v_lshlrev_b32_e32 v93, 2, v18
	v_xor_b32_e32 v18, 4, v16
	v_cmp_lt_i32_e32 vcc, v18, v17
	v_mov_b64_e32 v[84:85], s[8:9]
	s_nop 0
	v_cndmask_b32_e32 v18, v16, v18, vcc
	v_lshlrev_b32_e32 v94, 2, v18
	v_xor_b32_e32 v18, 8, v16
	v_cmp_lt_i32_e32 vcc, v18, v17
	s_nop 1
	v_cndmask_b32_e32 v18, v16, v18, vcc
	v_lshlrev_b32_e32 v95, 2, v18
	v_xor_b32_e32 v18, 16, v16
	v_cmp_lt_i32_e32 vcc, v18, v17
	s_nop 1
	v_cndmask_b32_e32 v18, v16, v18, vcc
	s_waitcnt vmcnt(0)
	v_lshlrev_b32_e32 v96, 2, v18
	v_xor_b32_e32 v18, 32, v16
	v_cmp_lt_i32_e32 vcc, v18, v17
	s_nop 1
	v_cndmask_b32_e32 v16, v16, v18, vcc
	v_lshlrev_b32_e32 v97, 2, v16
	v_lshlrev_b64 v[16:17], 12, v[80:81]
	v_and_b32_e32 v18, 63, v170
	v_lshl_or_b32 v16, v18, 4, v16
	v_lshl_add_u64 v[16:17], s[6:7], 0, v[16:17]
	v_lshl_add_u64 v[82:83], v[16:17], 0, s[2:3]
	s_lshl_b64 s[2:3], s[0:1], 12
	s_mov_b32 s6, 0x3a800000
	s_mov_b32 s1, 0x800000
	s_movk_i32 s7, 0x41ff
